# v38 + FFN-down weight transposes of layers 1-3 moved out of the prologue into the idle half of the previous layer's FFN-up 9th round (hand-written pipelined transpose loop)
# speedup vs baseline: 1.0124x; 1.0021x over previous
.LBB0_35:
	s_or_b64 exec, exec, s[4:5]
	s_lshl_b32 s4, s14, 14
	s_add_i32 s4, s4, 0
	s_add_u32 s19, s16, 0x76b32000
	s_addc_u32 s23, s17, 0
	s_add_u32 s25, s16, 0x6eb32000
	s_addc_u32 s40, s17, 0
	s_add_u32 s41, s16, 0x6ab32000
	s_addc_u32 s42, s17, 0
	s_add_u32 s43, s16, 0x6bb32000
	s_addc_u32 s44, s17, 0
	s_add_u32 s13, s16, 0x69332000
	s_addc_u32 s15, s17, 0
	s_add_u32 s45, s16, 0x68732000
	s_addc_u32 s47, s17, 0
	s_add_u32 s48, s16, 0x68132000
	s_addc_u32 s49, s17, 0
	s_add_u32 s50, s16, 0x67732000
	s_addc_u32 s51, s17, 0
	v_lshrrev_b32_e32 v40, 3, v1
	s_add_u32 s52, s16, 0x69b32000
	v_mul_u32_u24_e32 v5, 0x420, v10
	v_lshlrev_b32_e32 v6, 2, v40
	s_addc_u32 s53, s17, 0
	v_lshl_add_u32 v3, v10, 4, s4
	v_add3_u32 v51, s4, v5, v6
	s_lshl_b32 s54, s46, 10
	s_lshl_b32 s4, s14, 7
	s_add_i32 s54, s54, s4
	s_lshl_b32 s4, s14, 6
	v_lshlrev_b32_e32 v34, 2, v1
	s_add_i32 s56, s56, s4
	s_lshl_b32 s4, s46, 8
	s_lshl_b32 s5, s14, 5
	v_and_b32_e32 v2, 28, v34
	v_mov_b32_e32 v43, 0
	v_mul_u32_u24_e32 v4, 0x84, v40
	v_or_b32_e32 v35, 8, v40
	v_or_b32_e32 v49, 16, v40
	v_or_b32_e32 v50, 24, v40
	v_lshlrev_b32_e32 v52, 1, v40
	v_mov_b32_e32 v5, 0x800
	s_add_i32 s57, s4, s5
	s_mov_b32 s7, 0
	v_or_b32_e32 v53, 0x800, v52
	v_lshl_or_b32 v54, v35, 1, v5
	v_lshl_or_b32 v55, v49, 1, v5
	v_lshl_or_b32 v56, v50, 1, v5
	v_mov_b32_e32 v41, v43
	s_lshl_b32 s55, s58, 10
	s_addk_i32 s57, 0xfe00
	s_lshl_b32 s58, s58, 8
	v_lshlrev_b32_e32 v42, 2, v2
	s_movk_i32 s59, 0x1000
	s_movk_i32 s60, 0x7ff
	s_mov_b32 s61, 0x2aaaaaab
	s_movk_i32 s62, 0xc0
	s_movk_i32 s63, 0x7f
	s_movk_i32 s64, 0xff40
	s_movk_i32 s65, 0x1ff
	v_add_u32_e32 v57, v3, v4
	s_mov_b32 s66, 1
	s_branch .LBB0_37
.LBB0_36:
	s_add_i32 s66, s66, 1
	s_cmp_eq_u32 s66, 2
	s_cselect_b32 s66, 3, s66
	s_cmp_eq_u32 s66, 4
	s_cselect_b32 s66, 5, s66
	s_cmp_eq_u32 s66, 26
	s_cbranch_scc1 .LBB0_201

.LBB0_1964:
	s_waitcnt vmcnt(0)
	v_readlane_b32 s86, v255, 26
	v_readlane_b32 s87, v255, 27
	s_barrier
	v_readlane_b32 s2, v254, 0
	v_readlane_b32 s3, v255, 24
	s_load_dword s4, s[86:87], 0xc0
	s_load_dwordx2 s[6:7], s[86:87], 0x98
	s_load_dwordx2 s[8:9], s[86:87], 0xb0
	s_cmp_ge_u32 s3, 3
	s_cbranch_scc1 .Ldj_done
	s_waitcnt lgkmcnt(0)
	s_cmp_eq_u32 s4, 0x100
	s_cbranch_scc0 .Ldj_all
	s_cmp_lt_u32 s2, 0x80
	s_cbranch_scc1 .Ldj_done
	s_sub_u32 s2, s2, 0x80
	s_movk_i32 s4, 0x80
.Ldj_all:
	v_readfirstlane_b32 s5, v0
	s_lshr_b32 s5, s5, 6
	s_lshl_b32 s10, s2, 3
	s_add_u32 s10, s10, s5
	s_lshl_b32 s11, s4, 3
	s_add_u32 s3, s3, 1
	s_lshl_b32 s48, s3, 26
	s_add_u32 s6, s6, s48
	s_addc_u32 s7, s7, 0
	s_lshl_b32 s48, s3, 25
	s_add_u32 s8, s8, 0x76b32000
	s_addc_u32 s9, s9, 0
	s_add_u32 s8, s8, s48
	s_addc_u32 s9, s9, 0
	v_mbcnt_lo_u32_b32 v41, -1, 0
	v_mbcnt_hi_u32_b32 v41, -1, v41
	v_lshrrev_b32_e32 v42, 3, v41
	v_and_b32_e32 v43, 7, v41
	v_lshlrev_b32_e32 v44, 13, v42
	v_lshl_add_u32 v44, v43, 4, v44
	v_add_u32_e32 v45, 0x10000, v44
	v_add_u32_e32 v46, 0x20000, v44
	v_add_u32_e32 v47, 0x30000, v44
	v_add_u32_e32 v48, 0x40000, v44
	v_add_u32_e32 v49, 0x50000, v44
	v_add_u32_e32 v50, 0x60000, v44
	v_add_u32_e32 v51, 0x70000, v44
	s_lshl_b32 s49, s5, 14
	v_mul_u32_u24_e32 v52, 0x84, v42
	v_lshl_add_u32 v52, v43, 4, v52
	v_add_u32_e32 v52, s49, v52
	v_mul_u32_u24_e32 v53, 0x420, v43
	v_lshl_add_u32 v53, v42, 2, v53
	v_add_u32_e32 v53, s49, v53
	v_lshlrev_b32_e32 v54, 14, v42
	v_lshl_add_u32 v54, v43, 4, v54
	v_add_u32_e32 v55, 0x20000, v54
	v_add_u32_e32 v56, 0x40000, v54
	v_add_u32_e32 v57, 0x60000, v54
	s_cmp_ge_u32 s10, 0x2000
	s_cbranch_scc1 .Ldj_done
	s_lshr_b32 s54, s10, 6
	s_and_b32 s55, s10, 63
	s_lshl_b32 s56, s54, 19
	s_lshl_b32 s57, s55, 7
	s_add_u32 s56, s56, s57
	s_add_u32 s50, s6, s56
	s_addc_u32 s51, s7, 0
	global_load_dwordx4 v[58:61], v44, s[50:51] nt
	global_load_dwordx4 v[62:65], v45, s[50:51] nt
	global_load_dwordx4 v[66:69], v46, s[50:51] nt
	global_load_dwordx4 v[70:73], v47, s[50:51] nt
	global_load_dwordx4 v[74:77], v48, s[50:51] nt
	global_load_dwordx4 v[78:81], v49, s[50:51] nt
	global_load_dwordx4 v[82:85], v50, s[50:51] nt
	global_load_dwordx4 v[86:89], v51, s[50:51] nt
	s_add_u32 s71, s10, s11
	s_cmp_ge_u32 s71, 0x2000
	s_cbranch_scc1 .Ldj_first0
	s_lshr_b32 s54, s71, 6
	s_and_b32 s55, s71, 63
	s_lshl_b32 s56, s54, 19
	s_lshl_b32 s57, s55, 7
	s_add_u32 s56, s56, s57
	s_add_u32 s50, s6, s56
	s_addc_u32 s51, s7, 0
	global_load_dwordx4 v[90:93], v44, s[50:51] nt
	global_load_dwordx4 v[94:97], v45, s[50:51] nt
	global_load_dwordx4 v[98:101], v46, s[50:51] nt
	global_load_dwordx4 v[102:105], v47, s[50:51] nt
	global_load_dwordx4 v[106:109], v48, s[50:51] nt
	global_load_dwordx4 v[110:113], v49, s[50:51] nt
	global_load_dwordx4 v[114:117], v50, s[50:51] nt
	global_load_dwordx4 v[118:121], v51, s[50:51] nt
	s_waitcnt vmcnt(8)
	s_branch .Ldj_loop

.Ldj_loop:
	s_lshr_b32 s54, s10, 6
	s_and_b32 s55, s10, 63
	s_lshl_b32 s58, s55, 19
	s_lshl_b32 s59, s54, 7
	s_add_u32 s58, s58, s59
	ds_write_b32 v52, v58 offset:0
	ds_write_b32 v52, v59 offset:4
	ds_write_b32 v52, v60 offset:8
	ds_write_b32 v52, v61 offset:12
	ds_write_b32 v52, v62 offset:1056
	ds_write_b32 v52, v63 offset:1060
	ds_write_b32 v52, v64 offset:1064
	ds_write_b32 v52, v65 offset:1068
	ds_write_b32 v52, v66 offset:2112
	ds_write_b32 v52, v67 offset:2116
	ds_write_b32 v52, v68 offset:2120
	ds_write_b32 v52, v69 offset:2124
	ds_write_b32 v52, v70 offset:3168
	ds_write_b32 v52, v71 offset:3172
	ds_write_b32 v52, v72 offset:3176
	ds_write_b32 v52, v73 offset:3180
	ds_write_b32 v52, v74 offset:4224
	ds_write_b32 v52, v75 offset:4228
	ds_write_b32 v52, v76 offset:4232
	ds_write_b32 v52, v77 offset:4236
	ds_write_b32 v52, v78 offset:5280
	ds_write_b32 v52, v79 offset:5284
	ds_write_b32 v52, v80 offset:5288
	ds_write_b32 v52, v81 offset:5292
	ds_write_b32 v52, v82 offset:6336
	ds_write_b32 v52, v83 offset:6340
	ds_write_b32 v52, v84 offset:6344
	ds_write_b32 v52, v85 offset:6348
	ds_write_b32 v52, v86 offset:7392
	ds_write_b32 v52, v87 offset:7396
	ds_write_b32 v52, v88 offset:7400
	ds_write_b32 v52, v89 offset:7404
	s_waitcnt lgkmcnt(0)
	s_add_u32 s10, s71, s11
	s_cmp_ge_u32 s10, 0x2000
	s_cbranch_scc1 .Ldj_nopfa
	s_lshr_b32 s54, s10, 6
	s_and_b32 s55, s10, 63
	s_lshl_b32 s56, s54, 19
	s_lshl_b32 s57, s55, 7
	s_add_u32 s56, s56, s57
	s_add_u32 s50, s6, s56
	s_addc_u32 s51, s7, 0
	global_load_dwordx4 v[58:61], v44, s[50:51] nt
	global_load_dwordx4 v[62:65], v45, s[50:51] nt
	global_load_dwordx4 v[66:69], v46, s[50:51] nt
	global_load_dwordx4 v[70:73], v47, s[50:51] nt
	global_load_dwordx4 v[74:77], v48, s[50:51] nt
	global_load_dwordx4 v[78:81], v49, s[50:51] nt
	global_load_dwordx4 v[82:85], v50, s[50:51] nt
	global_load_dwordx4 v[86:89], v51, s[50:51] nt
.Ldj_nopfa:
	ds_read2_b32 v[122:123], v53 offset0:0 offset1:33
	ds_read2_b32 v[124:125], v53 offset0:66 offset1:99
	ds_read2_b32 v[126:127], v53 offset0:132 offset1:165
	ds_read2_b32 v[128:129], v53 offset0:198 offset1:231
	ds_read2_b32 v[130:131], v53 offset0:8 offset1:41
	ds_read2_b32 v[132:133], v53 offset0:74 offset1:107
	ds_read2_b32 v[134:135], v53 offset0:140 offset1:173
	ds_read2_b32 v[136:137], v53 offset0:206 offset1:239
	ds_read2_b32 v[138:139], v53 offset0:16 offset1:49
	ds_read2_b32 v[140:141], v53 offset0:82 offset1:115
	ds_read2_b32 v[142:143], v53 offset0:148 offset1:181
	ds_read2_b32 v[144:145], v53 offset0:214 offset1:247
	ds_read2_b32 v[146:147], v53 offset0:24 offset1:57
	ds_read2_b32 v[148:149], v53 offset0:90 offset1:123
	ds_read2_b32 v[180:181], v53 offset0:156 offset1:189
	ds_read2_b32 v[182:183], v53 offset0:222 offset1:255
	s_waitcnt lgkmcnt(0)
	v_cvt_pk_bf16_f32 v184, v122, v123
	v_cvt_pk_bf16_f32 v185, v124, v125
	v_cvt_pk_bf16_f32 v186, v126, v127
	v_cvt_pk_bf16_f32 v187, v128, v129
	v_cvt_pk_bf16_f32 v188, v130, v131
	v_cvt_pk_bf16_f32 v189, v132, v133
	v_cvt_pk_bf16_f32 v190, v134, v135
	v_cvt_pk_bf16_f32 v191, v136, v137
	v_cvt_pk_bf16_f32 v192, v138, v139
	v_cvt_pk_bf16_f32 v193, v140, v141
	v_cvt_pk_bf16_f32 v194, v142, v143
	v_cvt_pk_bf16_f32 v195, v144, v145
	v_cvt_pk_bf16_f32 v196, v146, v147
	v_cvt_pk_bf16_f32 v197, v148, v149
	v_cvt_pk_bf16_f32 v198, v180, v181
	v_cvt_pk_bf16_f32 v199, v182, v183
	v_add_u32_e32 v200, s58, v54
	v_add_u32_e32 v201, s58, v55
	v_add_u32_e32 v202, s58, v56
	v_add_u32_e32 v203, s58, v57
	global_store_dwordx4 v200, v[184:187], s[8:9]
	global_store_dwordx4 v201, v[188:191], s[8:9]
	global_store_dwordx4 v202, v[192:195], s[8:9]
	global_store_dwordx4 v203, v[196:199], s[8:9]
	s_cmp_ge_u32 s71, 0x2000
	s_cbranch_scc1 .Ldj_done
	s_cmp_ge_u32 s10, 0x2000
	s_cbranch_scc1 .Ldj_w4a
	s_waitcnt vmcnt(12)
	s_branch .Ldj_goa
.Ldj_w4a:
	s_waitcnt vmcnt(4)
.Ldj_goa:
	s_lshr_b32 s54, s71, 6
	s_and_b32 s55, s71, 63
	s_lshl_b32 s58, s55, 19
	s_lshl_b32 s59, s54, 7
	s_add_u32 s58, s58, s59
	ds_write_b32 v52, v90 offset:0
	ds_write_b32 v52, v91 offset:4
	ds_write_b32 v52, v92 offset:8
	ds_write_b32 v52, v93 offset:12
	ds_write_b32 v52, v94 offset:1056
	ds_write_b32 v52, v95 offset:1060
	ds_write_b32 v52, v96 offset:1064
	ds_write_b32 v52, v97 offset:1068
	ds_write_b32 v52, v98 offset:2112
	ds_write_b32 v52, v99 offset:2116
	ds_write_b32 v52, v100 offset:2120
	ds_write_b32 v52, v101 offset:2124
	ds_write_b32 v52, v102 offset:3168
	ds_write_b32 v52, v103 offset:3172
	ds_write_b32 v52, v104 offset:3176
	ds_write_b32 v52, v105 offset:3180
	ds_write_b32 v52, v106 offset:4224
	ds_write_b32 v52, v107 offset:4228
	ds_write_b32 v52, v108 offset:4232
	ds_write_b32 v52, v109 offset:4236
	ds_write_b32 v52, v110 offset:5280
	ds_write_b32 v52, v111 offset:5284
	ds_write_b32 v52, v112 offset:5288
	ds_write_b32 v52, v113 offset:5292
	ds_write_b32 v52, v114 offset:6336
	ds_write_b32 v52, v115 offset:6340
	ds_write_b32 v52, v116 offset:6344
	ds_write_b32 v52, v117 offset:6348
	ds_write_b32 v52, v118 offset:7392
	ds_write_b32 v52, v119 offset:7396
	ds_write_b32 v52, v120 offset:7400
	ds_write_b32 v52, v121 offset:7404
	s_waitcnt lgkmcnt(0)
	s_add_u32 s71, s10, s11
	s_cmp_ge_u32 s71, 0x2000
	s_cbranch_scc1 .Ldj_nopfb
	s_lshr_b32 s54, s71, 6
	s_and_b32 s55, s71, 63
	s_lshl_b32 s56, s54, 19
	s_lshl_b32 s57, s55, 7
	s_add_u32 s56, s56, s57
	s_add_u32 s50, s6, s56
	s_addc_u32 s51, s7, 0
	global_load_dwordx4 v[90:93], v44, s[50:51] nt
	global_load_dwordx4 v[94:97], v45, s[50:51] nt
	global_load_dwordx4 v[98:101], v46, s[50:51] nt
	global_load_dwordx4 v[102:105], v47, s[50:51] nt
	global_load_dwordx4 v[106:109], v48, s[50:51] nt
	global_load_dwordx4 v[110:113], v49, s[50:51] nt
	global_load_dwordx4 v[114:117], v50, s[50:51] nt
	global_load_dwordx4 v[118:121], v51, s[50:51] nt
.Ldj_nopfb:
	ds_read2_b32 v[122:123], v53 offset0:0 offset1:33
	ds_read2_b32 v[124:125], v53 offset0:66 offset1:99
	ds_read2_b32 v[126:127], v53 offset0:132 offset1:165
	ds_read2_b32 v[128:129], v53 offset0:198 offset1:231
	ds_read2_b32 v[130:131], v53 offset0:8 offset1:41
	ds_read2_b32 v[132:133], v53 offset0:74 offset1:107
	ds_read2_b32 v[134:135], v53 offset0:140 offset1:173
	ds_read2_b32 v[136:137], v53 offset0:206 offset1:239
	ds_read2_b32 v[138:139], v53 offset0:16 offset1:49
	ds_read2_b32 v[140:141], v53 offset0:82 offset1:115
	ds_read2_b32 v[142:143], v53 offset0:148 offset1:181
	ds_read2_b32 v[144:145], v53 offset0:214 offset1:247
	ds_read2_b32 v[146:147], v53 offset0:24 offset1:57
	ds_read2_b32 v[148:149], v53 offset0:90 offset1:123
	ds_read2_b32 v[180:181], v53 offset0:156 offset1:189
	ds_read2_b32 v[182:183], v53 offset0:222 offset1:255
	s_waitcnt lgkmcnt(0)
	v_cvt_pk_bf16_f32 v184, v122, v123
	v_cvt_pk_bf16_f32 v185, v124, v125
	v_cvt_pk_bf16_f32 v186, v126, v127
	v_cvt_pk_bf16_f32 v187, v128, v129
	v_cvt_pk_bf16_f32 v188, v130, v131
	v_cvt_pk_bf16_f32 v189, v132, v133
	v_cvt_pk_bf16_f32 v190, v134, v135
	v_cvt_pk_bf16_f32 v191, v136, v137
	v_cvt_pk_bf16_f32 v192, v138, v139
	v_cvt_pk_bf16_f32 v193, v140, v141
	v_cvt_pk_bf16_f32 v194, v142, v143
	v_cvt_pk_bf16_f32 v195, v144, v145
	v_cvt_pk_bf16_f32 v196, v146, v147
	v_cvt_pk_bf16_f32 v197, v148, v149
	v_cvt_pk_bf16_f32 v198, v180, v181
	v_cvt_pk_bf16_f32 v199, v182, v183
	v_add_u32_e32 v200, s58, v54
	v_add_u32_e32 v201, s58, v55
	v_add_u32_e32 v202, s58, v56
	v_add_u32_e32 v203, s58, v57
	global_store_dwordx4 v200, v[184:187], s[8:9]
	global_store_dwordx4 v201, v[188:191], s[8:9]
	global_store_dwordx4 v202, v[192:195], s[8:9]
	global_store_dwordx4 v203, v[196:199], s[8:9]
	s_cmp_ge_u32 s10, 0x2000
	s_cbranch_scc1 .Ldj_done
	s_cmp_ge_u32 s71, 0x2000
	s_cbranch_scc1 .Ldj_w4b
	s_waitcnt vmcnt(12)
	s_branch .Ldj_gob

.Ldj_done:
.LBB0_1965:
	s_load_dwordx4 s[8:11], s[86:87], 0xb0
	v_readlane_b32 s2, v254, 8
	v_readlane_b32 s3, v254, 9
	s_nor_b64 s[0:1], s[2:3], s[0:1]
	s_add_i32 s4, s80, 3
	s_waitcnt lgkmcnt(0)
	s_cmp_lt_i32 s4, s11
	s_cselect_b64 s[2:3], -1, 0
	s_and_b64 s[0:1], s[0:1], s[2:3]
	s_andn2_b64 vcc, exec, s[0:1]
	s_cbranch_vccnz .LBB0_2015
	s_waitcnt vmcnt(0)
	s_waitcnt vmcnt(0)
	s_barrier
	s_mov_b64 s[0:1], exec
	v_readlane_b32 s6, v255, 22
	v_readlane_b32 s7, v255, 23
	s_and_b64 s[6:7], s[0:1], s[6:7]
	s_mov_b64 exec, s[6:7]
	s_cbranch_execz .LBB0_2014
	v_readlane_b32 s5, v254, 10
	s_waitcnt vmcnt(0) expcnt(0) lgkmcnt(0)
	s_nop 0
	v_mov_b32_e32 v2, s5
	ds_read_b32 v4, v2
	ds_read_b32 v2, v2 offset:4
	s_waitcnt lgkmcnt(1)
	v_cmp_ne_u32_e32 vcc, 0, v4
	s_cbranch_vccnz .LBB0_1982
	v_readlane_b32 s8, v254, 2
	v_readlane_b32 s9, v254, 3
	s_load_dwordx2 s[6:7], s[8:9], 0x4
	s_load_dword s5, s[86:87], 0xc0
	s_waitcnt lgkmcnt(0)
	s_mul_i32 s5, s6, s5
	s_mul_i32 s5, s5, s7
	s_mov_b32 s6, 1
	s_branch .LBB0_1970
